# MLA LDS copy in the P*V chain with the five LDS addresses formed in front of the chain (one ds_write per MFMA gap)
# speedup vs baseline: 1.0083x; 1.0083x over previous
; #define LAS __attribute__((address_space(3)))
; template <int DQK, int DV, bool CAUSAL, int KT, bool PRIO>
; DI void attn_unit(const bf16_t* Qb, int qpitch, const bf16_t* Kb, int kpitch, const bf16_t* Vtb, int vpitch, bf16_t* Ob, int opitch, int q0, int nt, LAS unsigned char* lds, float kbound, const float* qgain, const int* qpos, float qscale) {
;     ...
;     auto lstore = [&](int buf) {
; #pragma unroll
;         for (int i = 0; i < NKR; ++i) { const int c = tid + i * 512; if (NKC % 512 == 0 || c < NKC) *(LAS u32x4*)(lds + buf * KBUF + (c / KCH) * KS + (c % KCH) * 16) = kreg[i]; }
; #pragma unroll
;         for (int i = 0; i < NVR; ++i) { const int c = tid + i * 512; LAS unsigned char* p = lds + VOFF + buf * VBUF + (c / VCH) * VS + (c % VCH) * 16;
;             *(LAS u32x2*)p = (u32x2){vreg[i].x, vreg[i].y}; *(LAS u32x2*)(p + 8) = (u32x2){vreg[i].z, vreg[i].w}; }
;     };
;     ...
;                     float ps = 0.f;
; #pragma unroll
;                     for (int i = 0; i < 16; ++i) { s0[i] = __builtin_amdgcn_exp2f(s0[i]); ps += s0[i]; asm volatile("" : "+v"(ps)); }
; #pragma unroll
;                     for (int i = 0; i < 16; ++i) { s1[i] = __builtin_amdgcn_exp2f(s1[i]); ps += s1[i]; asm volatile("" : "+v"(ps)); }
;                     lrun += ps;
;                     bf16x8 pf[4];
; #pragma unroll
;                     for (int sf = 0; sf < 2; ++sf) {
;                         u32x4 pw; pw.x = pk2(s0[8 * sf], s0[8 * sf + 1]); pw.y = pk2(s0[8 * sf + 2], s0[8 * sf + 3]); pw.z = pk2(s0[8 * sf + 4], s0[8 * sf + 5]); pw.w = pk2(s0[8 * sf + 6], s0[8 * sf + 7]); pf[sf] = __builtin_bit_cast(bf16x8, pw);
;                         u32x4 pv; pv.x = pk2(s1[8 * sf], s1[8 * sf + 1]); pv.y = pk2(s1[8 * sf + 2], s1[8 * sf + 3]); pv.z = pk2(s1[8 * sf + 4], s1[8 * sf + 5]); pv.w = pk2(s1[8 * sf + 6], s1[8 * sf + 7]); pf[2 + sf] = __builtin_bit_cast(bf16x8, pv);
;                     }
;                     __builtin_amdgcn_sched_barrier(0); __builtin_amdgcn_s_setprio(1); __builtin_amdgcn_sched_barrier(0);
; #pragma unroll
;                     for (int q4 = 0; q4 < 4; ++q4)
; #pragma unroll
;                         for (int d = 0; d < NDB; ++d) o[d] = MFMA32(vf[q4][d], pf[q4], o[d]);
;                     __builtin_amdgcn_sched_barrier(0); __builtin_amdgcn_s_setprio(0); __builtin_amdgcn_sched_barrier(0);
.LBB0_1514:
	s_nop 7
	v_exp_f32_e32 v14, v80
	v_exp_f32_e32 v15, v81
	v_exp_f32_e32 v80, v82
	v_exp_f32_e32 v81, v83
	v_add_f32_e32 v82, 0, v14
	v_exp_f32_e32 v83, v84
	v_add_f32_e32 v82, v15, v82
	v_exp_f32_e32 v84, v85
	v_add_f32_e32 v82, v80, v82
	v_exp_f32_e32 v85, v86
	v_add_f32_e32 v82, v81, v82
	v_exp_f32_e32 v86, v87
	v_add_f32_e32 v82, v83, v82
	v_exp_f32_e32 v87, v88
	v_add_f32_e32 v82, v84, v82
	v_exp_f32_e32 v88, v89
	v_add_f32_e32 v82, v85, v82
	v_exp_f32_e32 v89, v90
	v_add_f32_e32 v82, v86, v82
	v_exp_f32_e32 v90, v91
	v_add_f32_e32 v82, v87, v82
	v_exp_f32_e32 v91, v92
	v_add_f32_e32 v82, v88, v82
	v_exp_f32_e32 v92, v93
	v_add_f32_e32 v82, v89, v82
	v_exp_f32_e32 v93, v94
	v_add_f32_e32 v82, v90, v82
	v_exp_f32_e32 v94, v95
	v_add_f32_e32 v82, v91, v82
	v_exp_f32_e32 v95, v64
	v_add_f32_e32 v82, v92, v82
	v_exp_f32_e32 v194, v66
	v_add_f32_e32 v82, v93, v82
	v_exp_f32_e32 v195, v67
	v_add_f32_e32 v64, v94, v82
	v_exp_f32_e32 v82, v65
	v_exp_f32_e32 v197, v68
	v_add_f32_e32 v64, v95, v64
	v_exp_f32_e32 v198, v69
	v_add_f32_e32 v64, v82, v64
	v_exp_f32_e32 v199, v70
	v_add_f32_e32 v64, v194, v64
	v_exp_f32_e32 v71, v71
	v_add_f32_e32 v64, v195, v64
	v_exp_f32_e32 v200, v72
	v_add_f32_e32 v64, v197, v64
	v_exp_f32_e32 v201, v73
	v_add_f32_e32 v64, v198, v64
	v_exp_f32_e32 v202, v74
	v_add_f32_e32 v64, v199, v64
	v_exp_f32_e32 v203, v75
	v_add_f32_e32 v64, v71, v64
	v_exp_f32_e32 v204, v76
	v_add_f32_e32 v64, v200, v64
	v_exp_f32_e32 v205, v77
	v_add_f32_e32 v64, v201, v64
	v_exp_f32_e32 v206, v78
	v_add_f32_e32 v64, v202, v64
	v_exp_f32_e32 v79, v79
	v_add_f32_e32 v64, v203, v64
	v_cvt_pk_bf16_f32 v65, v80, v81
	v_add_f32_e32 v64, v204, v64
	v_cvt_pk_bf16_f32 v66, v83, v84
	v_add_f32_e32 v64, v205, v64
	v_cvt_pk_bf16_f32 v67, v85, v86
	v_add_f32_e32 v64, v206, v64
	v_cvt_pk_bf16_f32 v68, v95, v82
	v_add_f32_e32 v207, v79, v64
	v_cvt_pk_bf16_f32 v64, v14, v15
	v_cvt_pk_bf16_f32 v69, v194, v195
	v_cvt_pk_bf16_f32 v70, v197, v198
	v_cvt_pk_bf16_f32 v71, v199, v71
	v_cvt_pk_bf16_f32 v72, v87, v88
	v_cvt_pk_bf16_f32 v73, v89, v90
	v_cvt_pk_bf16_f32 v74, v91, v92
	v_cvt_pk_bf16_f32 v75, v93, v94
	v_cvt_pk_bf16_f32 v76, v200, v201
	v_cvt_pk_bf16_f32 v77, v202, v203
	v_cvt_pk_bf16_f32 v78, v204, v205
	v_cvt_pk_bf16_f32 v79, v206, v79
	s_xor_b32 s100, s75, 1
	s_mul_i32 s101, s100, 0x6800
	s_mulk_i32 s100, 0xdc00
	v_add3_u32 v250, s101, v178, v179
	v_add3_u32 v251, s101, v181, v182
	v_add3_u32 v252, s101, v183, v184
	s_add_i32 s101, s101, s100
	v_add_u32_e32 v253, s101, v185
	v_add_u32_e32 v254, s101, v187
	v_add3_u32 v253, v253, v186, s57
	v_add3_u32 v254, v254, v188, s57
	s_setprio 1
	s_waitcnt lgkmcnt(0)
	s_waitcnt vmcnt(0)
	v_mfma_f32_32x32x16_bf16 v[32:47], v[156:159], v[64:67], v[32:47]
	v_add_f32_e32 v0, v0, v207
	v_mfma_f32_32x32x16_bf16 v[16:31], v[152:155], v[64:67], v[16:31]
	ds_write_b128 v250, v[96:99]
	v_mfma_f32_32x32x16_bf16 v[32:47], v[140:143], v[72:75], v[32:47]
	ds_write_b128 v251, v[100:103]
	v_mfma_f32_32x32x16_bf16 v[16:31], v[148:151], v[72:75], v[16:31]
	ds_write_b128 v252, v[104:107]
	v_mfma_f32_32x32x16_bf16 v[32:47], v[144:147], v[68:71], v[32:47]
	ds_write2_b64 v253, v[108:109], v[110:111] offset1:2
	v_mfma_f32_32x32x16_bf16 v[16:31], v[10:13], v[68:71], v[16:31]
	ds_write2_b64 v254, v[112:113], v[114:115] offset1:2
	v_mfma_f32_32x32x16_bf16 v[32:47], v[6:9], v[76:79], v[32:47]
	v_mfma_f32_32x32x16_bf16 v[16:31], v[2:5], v[76:79], v[16:31]
	s_setprio 0
	s_branch .LBB0_1493
	s_nop 0
	s_nop 0
	s_nop 0
	s_nop 0
	s_nop 0
	s_nop 0
	s_nop 0
	s_nop 0
	s_nop 0
	s_nop 0
	s_nop 0
	s_nop 0
	s_nop 0
